# one static s_setprio 1 for waves 4-7 during the dense GQA units (re-test on the aligned base)
# baseline (speedup 1.0000x reference)
; __device__ __forceinline__ unsigned cvt_pk_bf16(float lo, float hi) { f32x2_t v = {lo, hi}; bf16x2_t r = __builtin_convertvector(v, bf16x2_t); return __builtin_bit_cast(unsigned, r); }
; __device__ __forceinline__ int opaque_v(int v) { asm volatile("" : "+v"(v)); return v; }
; __device__ __forceinline__ int crow(int r, int hi) { return (r & 3) + 8 * (r >> 2) + 4 * hi; }
; template <int MODE, int SDEPTH, bool SIMPLE>
; __device__ __forceinline__ void attn_body(const Unit& U, char* lds, const int tid) {
;     ...
;   if (hi == 0) li_l[r32] = l_reg; asm volatile("s_waitcnt lgkmcnt(0)" ::: "memory");
;   if constexpr (MODE == 2) { if (hi == 0) U.LSE[(long)(wid * QBLK + r32) * U.ldl] = m_reg * SCALE + __logf(l_reg); }
;   __syncthreads();
;   constexpr int OP = 136;
;   bf16_t* ol = (bf16_t*)lds + wid * (32 * OP);
; #pragma unroll
;   for (int r = 0; r < 16; ++r) { const float rl = __builtin_amdgcn_rcpf(li_l[crow(r, hi)]); bf16_t* op = ol + crow(r, hi) * OP + r32;
; #pragma unroll
;     for (int d0 = 0; d0 < 4; ++d0) op[d0 * 32] = (bf16_t)(cvt_pk_bf16(o[d0][r] * rl, 0.f) & 0xffffu); }
; __global__ void __launch_bounds__(512) mega(Args a) {
;     ...
;       for (int i = 0;; ++i) {
;         const int un = i * G + cu; if (un >= NB * 8 * 32) break;
;         const int h = un & 7, qb = (un >> 3) & 31, b = un >> 8;
;         __syncthreads();
;         att::Unit U{};
;         const size_t tq = (size_t)b * SEQ + qb * 256;
;         U.Q = QBc + ((size_t)(b * 8 + h) * SEQ + qb * 256) * 128; U.K = KBc + (size_t)(b * 2 + (h >> 2)) * SEQ * 128; U.V = VBc + (size_t)(b * 2 + (h >> 2)) * SEQ * 128;
;         U.ldq = 128; U.ldk = 128; U.NT = SEQ / 64;
;         U.O = Y + tq * YW + 1024 + h * 128; U.ldo = YW; U.Z = PROJ + tq * NIN + C_ZB + h * 128; U.ldz = NIN;
;         att::attn_body<0, 2, false>(U, shm, opaque_v(tid));
.LBB0_195:
	s_or_b64 exec, exec, s[2:3]
	s_cmpk_gt_i32 s57, 0x1ff
	s_cbranch_scc1 .LBB0_217
	s_add_u32 s17, s0, 0x42000000
	s_addc_u32 s25, s1, 0
	s_add_u32 s58, s0, 0x44000000
	s_addc_u32 s59, s1, 0
	s_add_u32 s60, s0, 0x44800000
	s_addc_u32 s61, s1, 0
	v_readlane_b32 s0, v251, 4
	s_add_u32 s10, s0, s28
	v_readlane_b32 s0, v251, 5
	s_addc_u32 s11, s0, 0
	s_mov_b32 s40, 0
	s_mov_b32 s28, s57
	s_mov_b32 s0, s57
	s_mov_b32 s62, 0
	v_writelane_b32 v250, s4, 16
	v_writelane_b32 v250, s5, 17
	v_writelane_b32 v250, s6, 18
	v_writelane_b32 v250, s7, 19
	v_writelane_b32 v250, s66, 20
	v_writelane_b32 v250, s67, 21
	v_readfirstlane_b32 s1, v225
	s_nop 3
	s_cmp_lt_u32 s1, 0x100
	s_cbranch_scc1 .Lgq_prio_done
	s_setprio 1
.Lgq_prio_done:
	s_branch .LBB0_198
.LBB0_197:
	s_or_b64 exec, exec, s[0:1]
	s_ashr_i32 s31, s30, 31
	s_lshl_b64 s[0:1], s[30:31], 13
	s_or_b32 s0, s0, s19
	s_mul_i32 s2, s1, 0x1400
	s_mul_hi_u32 s3, s0, 0x1400
	s_add_i32 s3, s3, s2
	s_mul_i32 s2, s0, 0x1400
	s_add_u32 s2, s38, s2
	s_mul_i32 s1, s1, 0x8c00
	s_mul_hi_u32 s15, s0, 0x8c00
	v_add_u32_e32 v65, v185, v192
	s_addc_u32 s3, s39, s3
	s_add_i32 s15, s15, s1
	s_mul_i32 s0, s0, 0x8c00
	s_waitcnt lgkmcnt(0)
	s_waitcnt lgkmcnt(0)
	s_barrier
	ds_read_b128 v[66:69], v65
	s_add_u32 s19, s8, s0
	s_addc_u32 s15, s9, s15
	s_lshl_b32 s16, s16, 8
	s_add_u32 s0, s2, s16
	s_addc_u32 s1, s3, 0
	s_add_u32 s2, s19, s16
	s_waitcnt lgkmcnt(0)
	v_rcp_f32_e32 v66, v66
	s_addc_u32 s3, s15, 0
	s_movk_i32 s15, 0x2200
	v_mul_lo_u32 v64, v184, s15
	v_add_u32_e32 v64, 0, v64
	v_lshl_add_u32 v70, v183, 1, v64
	s_movk_i32 s15, 0x440
	v_mul_f32_e32 v0, v0, v66
	v_mad_u32_u24 v71, v182, s15, v70
	v_cvt_pk_bf16_f32 v0, v0, s0
	ds_write_b16 v71, v0
	v_mul_f32_e32 v0, v48, v66
	v_cvt_pk_bf16_f32 v0, v0, s0
	ds_write_b16 v71, v0 offset:64
	v_mul_f32_e32 v0, v32, v66
	v_cvt_pk_bf16_f32 v0, v0, s0
	v_rcp_f32_e32 v32, v67
	ds_write_b16 v71, v0 offset:128
	v_mul_f32_e32 v0, v16, v66
	v_cvt_pk_bf16_f32 v0, v0, s0
	ds_write_b16 v71, v0 offset:192
	v_lshl_or_b32 v0, v182, 2, 1
	s_movk_i32 s15, 0x110
	v_mad_u32_u24 v16, v0, s15, v70
	v_mul_f32_e32 v0, v1, v32
	v_cvt_pk_bf16_f32 v0, v0, s0
	ds_write_b16 v16, v0
	v_mul_f32_e32 v0, v49, v32
	v_cvt_pk_bf16_f32 v0, v0, s0
	ds_write_b16 v16, v0 offset:64
	v_mul_f32_e32 v0, v33, v32
	v_cvt_pk_bf16_f32 v0, v0, s0
	ds_write_b16 v16, v0 offset:128
	v_mul_f32_e32 v0, v17, v32
	v_cvt_pk_bf16_f32 v0, v0, s0
	ds_write_b16 v16, v0 offset:192
	v_rcp_f32_e32 v0, v68
	v_lshlrev_b32_e32 v192, 1, v176
	s_add_i32 s62, s62, 1
	s_add_i32 s28, s28, s56
	v_mul_f32_e32 v1, v2, v0
	v_cvt_pk_bf16_f32 v1, v1, s0
	ds_write_b16 v16, v1 offset:272
	v_mul_f32_e32 v1, v50, v0
	v_cvt_pk_bf16_f32 v1, v1, s0
	ds_write_b16 v16, v1 offset:336
	v_mul_f32_e32 v1, v34, v0
	v_mul_f32_e32 v0, v18, v0
	v_cvt_pk_bf16_f32 v0, v0, s0
	ds_write_b16 v16, v0 offset:464
	v_rcp_f32_e32 v0, v69
	v_cvt_pk_bf16_f32 v1, v1, s0
	ds_write_b16 v16, v1 offset:400
	s_movk_i32 s69, 0x1400
	v_mul_f32_e32 v1, v3, v0
	v_cvt_pk_bf16_f32 v1, v1, s0
	ds_write_b16 v16, v1 offset:544
	v_mul_f32_e32 v1, v51, v0
	v_cvt_pk_bf16_f32 v1, v1, s0
	ds_write_b16 v16, v1 offset:608
	v_mul_f32_e32 v1, v35, v0
	v_mul_f32_e32 v0, v19, v0
	v_cvt_pk_bf16_f32 v1, v1, s0
	v_cvt_pk_bf16_f32 v0, v0, s0
	ds_write_b16 v16, v1 offset:672
	ds_write_b16 v16, v0 offset:736
	ds_read_b128 v[0:3], v65 offset:32
	s_waitcnt lgkmcnt(0)
	v_rcp_f32_e32 v0, v0
	s_nop 0
	v_mul_f32_e32 v4, v4, v0
	v_cvt_pk_bf16_f32 v4, v4, s0
	ds_write_b16 v16, v4 offset:1904
	v_mul_f32_e32 v4, v52, v0
	v_cvt_pk_bf16_f32 v4, v4, s0
	ds_write_b16 v16, v4 offset:1968
	v_mul_f32_e32 v4, v36, v0
	v_mul_f32_e32 v0, v20, v0
	v_cvt_pk_bf16_f32 v0, v0, s0
	ds_write_b16 v16, v0 offset:2096
	v_rcp_f32_e32 v0, v1
	v_cvt_pk_bf16_f32 v4, v4, s0
	ds_write_b16 v16, v4 offset:2032
	v_mul_f32_e32 v1, v5, v0
	v_cvt_pk_bf16_f32 v1, v1, s0
	ds_write_b16 v16, v1 offset:2176
	v_mul_f32_e32 v1, v53, v0
	v_cvt_pk_bf16_f32 v1, v1, s0
	ds_write_b16 v16, v1 offset:2240
	v_mul_f32_e32 v1, v37, v0
	v_mul_f32_e32 v0, v21, v0
	v_cvt_pk_bf16_f32 v0, v0, s0
	ds_write_b16 v16, v0 offset:2368
	v_rcp_f32_e32 v0, v2
	v_cvt_pk_bf16_f32 v1, v1, s0
	ds_write_b16 v16, v1 offset:2304
	v_mul_f32_e32 v1, v6, v0
	v_cvt_pk_bf16_f32 v1, v1, s0
	ds_write_b16 v16, v1 offset:2448
	v_mul_f32_e32 v1, v54, v0
	v_cvt_pk_bf16_f32 v1, v1, s0
	ds_write_b16 v16, v1 offset:2512
	v_mul_f32_e32 v1, v38, v0
	v_mul_f32_e32 v0, v22, v0
	v_cvt_pk_bf16_f32 v0, v0, s0
	ds_write_b16 v16, v0 offset:2640
	v_rcp_f32_e32 v0, v3
	v_cvt_pk_bf16_f32 v1, v1, s0
	ds_write_b16 v16, v1 offset:2576
	v_mul_f32_e32 v1, v7, v0
	v_cvt_pk_bf16_f32 v1, v1, s0
	ds_write_b16 v16, v1 offset:2720
	v_mul_f32_e32 v1, v55, v0
	v_cvt_pk_bf16_f32 v1, v1, s0
	ds_write_b16 v16, v1 offset:2784
	v_mul_f32_e32 v1, v39, v0
	v_mul_f32_e32 v0, v23, v0
	v_cvt_pk_bf16_f32 v1, v1, s0
	v_cvt_pk_bf16_f32 v0, v0, s0
	ds_write_b16 v16, v1 offset:2848
	ds_write_b16 v16, v0 offset:2912
	ds_read_b128 v[0:3], v65 offset:64
	s_waitcnt lgkmcnt(0)
; __device__ __forceinline__ unsigned cvt_pk_bf16(float lo, float hi) { f32x2_t v = {lo, hi}; bf16x2_t r = __builtin_convertvector(v, bf16x2_t); return __builtin_bit_cast(unsigned, r); }
; __device__ __forceinline__ float bf_lo(unsigned w) { return __uint_as_float(w << 16); }
; __device__ __forceinline__ float bf_hi(unsigned w) { return __uint_as_float(w & 0xffff0000u); }
; __device__ __forceinline__ int crow(int r, int hi) { return (r & 3) + 8 * (r >> 2) + 4 * hi; }
; template <int MODE, int SDEPTH, bool SIMPLE>
; __device__ __forceinline__ void attn_body(const Unit& U, char* lds, const int tid) {
;     ...
;   for (int r = 0; r < 16; ++r) { const float rl = __builtin_amdgcn_rcpf(li_l[crow(r, hi)]); bf16_t* op = ol + crow(r, hi) * OP + r32;
; #pragma unroll
;     for (int d0 = 0; d0 < 4; ++d0) op[d0 * 32] = (bf16_t)(cvt_pk_bf16(o[d0][r] * rl, 0.f) & 0xffffu); }
;   asm volatile("s_waitcnt lgkmcnt(0)" ::: "memory");
;   { const int cc = (lane & 15) * 8, rb = lane >> 4;
;     u32x4 zz[8];
;     if constexpr (MODE != 2) {
; #pragma unroll
;       for (int i = 0; i < 8; ++i) zz[i] = *(const u32x4*)(U.Z + (long)(wid * QBLK + rb + 4 * i) * U.ldz + cc);
;     }
; #pragma unroll
;     for (int i = 0; i < 8; ++i) { const int row = rb + 4 * i; const long orow = wid * QBLK + row;
;       u32x4 v = *(const u32x4*)(ol + row * OP + cc);
;       if constexpr (MODE != 2) { const u32x4 z = zz[i];
; #pragma unroll
;         for (int q = 0; q < 4; ++q) v[q] = cvt_pk_bf16(bf_lo(v[q]) * bf_lo(z[q]), bf_hi(v[q]) * bf_hi(z[q])); }
;       *(u32x4*)(U.O + orow * U.ldo + cc) = v; } }
	v_rcp_f32_e32 v0, v0
	s_nop 0
	v_mul_f32_e32 v4, v8, v0
	v_cvt_pk_bf16_f32 v4, v4, s0
	ds_write_b16 v16, v4 offset:4080
	v_mul_f32_e32 v4, v56, v0
	v_cvt_pk_bf16_f32 v4, v4, s0
	ds_write_b16 v16, v4 offset:4144
	v_mul_f32_e32 v4, v40, v0
	v_mul_f32_e32 v0, v24, v0
	v_cvt_pk_bf16_f32 v0, v0, s0
	ds_write_b16 v16, v0 offset:4272
	v_rcp_f32_e32 v0, v1
	v_cvt_pk_bf16_f32 v4, v4, s0
	ds_write_b16 v16, v4 offset:4208
	v_mul_f32_e32 v1, v9, v0
	v_cvt_pk_bf16_f32 v1, v1, s0
	ds_write_b16 v16, v1 offset:4352
	v_mul_f32_e32 v1, v57, v0
	v_cvt_pk_bf16_f32 v1, v1, s0
	ds_write_b16 v16, v1 offset:4416
	v_mul_f32_e32 v1, v41, v0
	v_mul_f32_e32 v0, v25, v0
	v_cvt_pk_bf16_f32 v0, v0, s0
	ds_write_b16 v16, v0 offset:4544
	v_rcp_f32_e32 v0, v2
	v_cvt_pk_bf16_f32 v1, v1, s0
	ds_write_b16 v16, v1 offset:4480
	v_mul_f32_e32 v1, v10, v0
	v_cvt_pk_bf16_f32 v1, v1, s0
	ds_write_b16 v16, v1 offset:4624
	v_mul_f32_e32 v1, v58, v0
	v_cvt_pk_bf16_f32 v1, v1, s0
	ds_write_b16 v16, v1 offset:4688
	v_mul_f32_e32 v1, v42, v0
	v_mul_f32_e32 v0, v26, v0
	v_cvt_pk_bf16_f32 v0, v0, s0
	ds_write_b16 v16, v0 offset:4816
	v_rcp_f32_e32 v0, v3
	v_cvt_pk_bf16_f32 v1, v1, s0
	ds_write_b16 v16, v1 offset:4752
	v_mul_f32_e32 v1, v11, v0
	v_cvt_pk_bf16_f32 v1, v1, s0
	ds_write_b16 v16, v1 offset:4896
	v_mul_f32_e32 v1, v59, v0
	v_cvt_pk_bf16_f32 v1, v1, s0
	ds_write_b16 v16, v1 offset:4960
	v_mul_f32_e32 v1, v43, v0
	v_mul_f32_e32 v0, v27, v0
	v_cvt_pk_bf16_f32 v1, v1, s0
	v_cvt_pk_bf16_f32 v0, v0, s0
	ds_write_b16 v16, v1 offset:5024
	ds_write_b16 v16, v0 offset:5088
	ds_read_b128 v[0:3], v65 offset:96
	s_waitcnt lgkmcnt(0)
	v_rcp_f32_e32 v0, v0
	s_nop 0
	v_mul_f32_e32 v4, v12, v0
	v_cvt_pk_bf16_f32 v4, v4, s0
	ds_write_b16 v16, v4 offset:6256
	v_mul_f32_e32 v4, v60, v0
	v_cvt_pk_bf16_f32 v4, v4, s0
	ds_write_b16 v16, v4 offset:6320
	v_mul_f32_e32 v4, v44, v0
	v_mul_f32_e32 v0, v28, v0
	v_cvt_pk_bf16_f32 v0, v0, s0
	ds_write_b16 v16, v0 offset:6448
	v_rcp_f32_e32 v0, v1
	v_cvt_pk_bf16_f32 v4, v4, s0
	v_lshrrev_b32_e32 v28, 4, v181
	ds_write_b16 v16, v4 offset:6384
	v_mul_f32_e32 v1, v13, v0
	v_cvt_pk_bf16_f32 v1, v1, s0
	ds_write_b16 v16, v1 offset:6528
	v_mul_f32_e32 v1, v61, v0
	v_cvt_pk_bf16_f32 v1, v1, s0
	ds_write_b16 v16, v1 offset:6592
	v_mul_f32_e32 v1, v45, v0
	v_mul_f32_e32 v0, v29, v0
	v_cvt_pk_bf16_f32 v0, v0, s0
	ds_write_b16 v16, v0 offset:6720
	v_rcp_f32_e32 v0, v2
	v_cvt_pk_bf16_f32 v1, v1, s0
	ds_write_b16 v16, v1 offset:6656
	v_mul_f32_e32 v1, v14, v0
	v_cvt_pk_bf16_f32 v1, v1, s0
	ds_write_b16 v16, v1 offset:6800
	v_mul_f32_e32 v1, v62, v0
	v_cvt_pk_bf16_f32 v1, v1, s0
	ds_write_b16 v16, v1 offset:6864
	v_mul_f32_e32 v1, v46, v0
	v_mul_f32_e32 v0, v30, v0
	v_cvt_pk_bf16_f32 v0, v0, s0
	ds_write_b16 v16, v0 offset:6992
	v_rcp_f32_e32 v0, v3
	v_cvt_pk_bf16_f32 v1, v1, s0
	ds_write_b16 v16, v1 offset:6928
	v_or_b32_e32 v46, v28, v180
	v_mul_f32_e32 v1, v15, v0
	v_cvt_pk_bf16_f32 v1, v1, s0
	ds_write_b16 v16, v1 offset:7072
	v_mul_f32_e32 v1, v63, v0
	v_cvt_pk_bf16_f32 v1, v1, s0
	ds_write_b16 v16, v1 offset:7136
	v_mul_f32_e32 v1, v47, v0
	v_mul_f32_e32 v0, v31, v0
	v_cvt_pk_bf16_f32 v1, v1, s0
	v_cvt_pk_bf16_f32 v0, v0, s0
	ds_write_b16 v16, v1 offset:7200
	ds_write_b16 v16, v0 offset:7264
	v_lshl_add_u64 v[0:1], s[2:3], 0, v[192:193]
	s_mov_b64 s[2:3], 0x5000
	v_lshl_add_u64 v[0:1], v[0:1], 0, s[2:3]
	s_waitcnt lgkmcnt(0)
	v_mad_i64_i32 v[2:3], s[2:3], v46, s14, v[0:1]
	global_load_dwordx4 v[36:39], v[2:3], off
	v_or_b32_e32 v47, 4, v46
	v_mad_i64_i32 v[2:3], s[2:3], v47, s14, v[0:1]
	global_load_dwordx4 v[24:27], v[2:3], off
	v_or_b32_e32 v48, 8, v46
	v_mad_i64_i32 v[2:3], s[2:3], v48, s14, v[0:1]
	global_load_dwordx4 v[20:23], v[2:3], off
	v_or_b32_e32 v35, 12, v46
	v_mad_i64_i32 v[2:3], s[2:3], v35, s14, v[0:1]
	global_load_dwordx4 v[16:19], v[2:3], off
	v_or_b32_e32 v34, 16, v46
	v_mad_i64_i32 v[2:3], s[2:3], v34, s14, v[0:1]
	global_load_dwordx4 v[12:15], v[2:3], off
	v_mul_u32_u24_e32 v28, 0x110, v28
	v_or_b32_e32 v33, 20, v46
	v_add3_u32 v31, v64, v192, v28
	v_mad_i64_i32 v[2:3], s[2:3], v33, s14, v[0:1]
	ds_read_b128 v[40:43], v31
	global_load_dwordx4 v[8:11], v[2:3], off
	v_or_b32_e32 v32, 24, v46
	v_or_b32_e32 v30, 28, v46
	v_mad_i64_i32 v[2:3], s[2:3], v32, s14, v[0:1]
	s_waitcnt lgkmcnt(0)
	v_lshlrev_b32_e32 v28, 16, v40
	v_and_b32_e32 v29, 0xffff0000, v40
	v_mad_i64_i32 v[0:1], s[2:3], v30, s14, v[0:1]
	s_movk_i32 s2, 0x1400
	global_load_dwordx4 v[4:7], v[2:3], off
	s_waitcnt vmcnt(6)
	v_lshlrev_b32_e32 v44, 16, v36
	v_and_b32_e32 v45, 0xffff0000, v36
	v_pk_mul_f32 v[28:29], v[44:45], v[28:29]
	v_lshlrev_b32_e32 v40, 16, v37
	v_cvt_pk_bf16_f32 v36, v28, v29
	v_lshlrev_b32_e32 v28, 16, v41
	v_and_b32_e32 v29, 0xffff0000, v41
	v_and_b32_e32 v41, 0xffff0000, v37
	v_pk_mul_f32 v[28:29], v[40:41], v[28:29]
	v_lshlrev_b32_e32 v40, 16, v38
	v_cvt_pk_bf16_f32 v37, v28, v29
	v_lshlrev_b32_e32 v28, 16, v42
	v_and_b32_e32 v29, 0xffff0000, v42
	v_and_b32_e32 v41, 0xffff0000, v38
	v_pk_mul_f32 v[28:29], v[40:41], v[28:29]
	v_lshlrev_b32_e32 v40, 16, v39
	v_cvt_pk_bf16_f32 v38, v28, v29
	v_lshlrev_b32_e32 v28, 16, v43
	v_and_b32_e32 v29, 0xffff0000, v43
	v_and_b32_e32 v41, 0xffff0000, v39
	v_pk_mul_f32 v[28:29], v[40:41], v[28:29]
	global_load_dwordx4 v[0:3], v[0:1], off
	v_cvt_pk_bf16_f32 v39, v28, v29
	v_mov_b64_e32 v[28:29], s[0:1]
	v_mad_i64_i32 v[40:41], s[0:1], v46, s2, v[28:29]
	v_lshl_add_u64 v[40:41], v[40:41], 0, v[192:193]
	global_store_dwordx4 v[40:41], v[36:39], off offset:2048 sc1
	ds_read_b128 v[36:39], v31 offset:1088
	s_waitcnt vmcnt(7)
	v_lshlrev_b32_e32 v42, 16, v24
	v_and_b32_e32 v43, 0xffff0000, v24
	s_waitcnt lgkmcnt(0)
; __device__ __forceinline__ unsigned cvt_pk_bf16(float lo, float hi) { f32x2_t v = {lo, hi}; bf16x2_t r = __builtin_convertvector(v, bf16x2_t); return __builtin_bit_cast(unsigned, r); }
; __device__ __forceinline__ float bf_lo(unsigned w) { return __uint_as_float(w << 16); }
; __device__ __forceinline__ float bf_hi(unsigned w) { return __uint_as_float(w & 0xffff0000u); }
; template <int MODE, int SDEPTH, bool SIMPLE>
; __device__ __forceinline__ void attn_body(const Unit& U, char* lds, const int tid) {
;     ...
;     for (int i = 0; i < 8; ++i) { const int row = rb + 4 * i; const long orow = wid * QBLK + row;
;       u32x4 v = *(const u32x4*)(ol + row * OP + cc);
;       if constexpr (MODE != 2) { const u32x4 z = zz[i];
; #pragma unroll
;         for (int q = 0; q < 4; ++q) v[q] = cvt_pk_bf16(bf_lo(v[q]) * bf_lo(z[q]), bf_hi(v[q]) * bf_hi(z[q])); }
;       *(u32x4*)(U.O + orow * U.ldo + cc) = v; } }
	v_lshlrev_b32_e32 v40, 16, v36
	v_and_b32_e32 v41, 0xffff0000, v36
	v_pk_mul_f32 v[40:41], v[42:43], v[40:41]
	v_lshlrev_b32_e32 v36, 16, v37
	v_cvt_pk_bf16_f32 v24, v40, v41
	v_and_b32_e32 v37, 0xffff0000, v37
	v_lshlrev_b32_e32 v40, 16, v25
	v_and_b32_e32 v41, 0xffff0000, v25
	v_pk_mul_f32 v[36:37], v[40:41], v[36:37]
	v_lshlrev_b32_e32 v40, 16, v26
	v_cvt_pk_bf16_f32 v25, v36, v37
	v_lshlrev_b32_e32 v36, 16, v38
	v_and_b32_e32 v37, 0xffff0000, v38
	v_and_b32_e32 v41, 0xffff0000, v26
	v_pk_mul_f32 v[36:37], v[40:41], v[36:37]
	v_lshlrev_b32_e32 v38, 16, v27
	v_cvt_pk_bf16_f32 v26, v36, v37
	v_lshlrev_b32_e32 v36, 16, v39
	v_and_b32_e32 v37, 0xffff0000, v39
	v_and_b32_e32 v39, 0xffff0000, v27
	v_pk_mul_f32 v[36:37], v[38:39], v[36:37]
	s_waitcnt vmcnt(6)
	v_lshlrev_b32_e32 v38, 16, v20
	v_cvt_pk_bf16_f32 v27, v36, v37
	v_mad_i64_i32 v[36:37], s[0:1], v47, s2, v[28:29]
	v_lshl_add_u64 v[36:37], v[36:37], 0, v[192:193]
	global_store_dwordx4 v[36:37], v[24:27], off offset:2048 sc1
	ds_read_b128 v[24:27], v31 offset:2176
	v_and_b32_e32 v39, 0xffff0000, v20
	s_waitcnt lgkmcnt(0)
	v_lshlrev_b32_e32 v36, 16, v24
	v_and_b32_e32 v37, 0xffff0000, v24
	v_pk_mul_f32 v[36:37], v[38:39], v[36:37]
	v_lshlrev_b32_e32 v24, 16, v25
	v_cvt_pk_bf16_f32 v20, v36, v37
	v_and_b32_e32 v25, 0xffff0000, v25
	v_lshlrev_b32_e32 v36, 16, v21
	v_and_b32_e32 v37, 0xffff0000, v21
	v_pk_mul_f32 v[24:25], v[36:37], v[24:25]
	v_lshlrev_b32_e32 v36, 16, v22
	v_cvt_pk_bf16_f32 v21, v24, v25
	v_lshlrev_b32_e32 v24, 16, v26
	v_and_b32_e32 v25, 0xffff0000, v26
	v_and_b32_e32 v37, 0xffff0000, v22
	v_pk_mul_f32 v[24:25], v[36:37], v[24:25]
	v_lshlrev_b32_e32 v26, 16, v23
	v_cvt_pk_bf16_f32 v22, v24, v25
	v_lshlrev_b32_e32 v24, 16, v27
	v_and_b32_e32 v25, 0xffff0000, v27
	v_and_b32_e32 v27, 0xffff0000, v23
	v_pk_mul_f32 v[24:25], v[26:27], v[24:25]
	s_waitcnt vmcnt(6)
	v_lshlrev_b32_e32 v26, 16, v16
	v_cvt_pk_bf16_f32 v23, v24, v25
	v_mad_i64_i32 v[24:25], s[0:1], v48, s2, v[28:29]
	v_lshl_add_u64 v[24:25], v[24:25], 0, v[192:193]
	global_store_dwordx4 v[24:25], v[20:23], off offset:2048 sc1
	ds_read_b128 v[20:23], v31 offset:3264
	v_and_b32_e32 v27, 0xffff0000, v16
	s_waitcnt lgkmcnt(0)
	v_lshlrev_b32_e32 v24, 16, v20
	v_and_b32_e32 v25, 0xffff0000, v20
	v_pk_mul_f32 v[24:25], v[26:27], v[24:25]
	v_lshlrev_b32_e32 v20, 16, v21
	v_cvt_pk_bf16_f32 v16, v24, v25
	v_and_b32_e32 v21, 0xffff0000, v21
	v_lshlrev_b32_e32 v24, 16, v17
	v_and_b32_e32 v25, 0xffff0000, v17
	v_pk_mul_f32 v[20:21], v[24:25], v[20:21]
	v_lshlrev_b32_e32 v24, 16, v18
	v_cvt_pk_bf16_f32 v17, v20, v21
	v_lshlrev_b32_e32 v20, 16, v22
	v_and_b32_e32 v21, 0xffff0000, v22
	v_and_b32_e32 v25, 0xffff0000, v18
	v_pk_mul_f32 v[20:21], v[24:25], v[20:21]
	v_lshlrev_b32_e32 v22, 16, v19
	v_cvt_pk_bf16_f32 v18, v20, v21
	v_lshlrev_b32_e32 v20, 16, v23
	v_and_b32_e32 v21, 0xffff0000, v23
	v_and_b32_e32 v23, 0xffff0000, v19
	v_pk_mul_f32 v[20:21], v[22:23], v[20:21]
	s_waitcnt vmcnt(6)
	v_lshlrev_b32_e32 v22, 16, v12
	v_cvt_pk_bf16_f32 v19, v20, v21
	v_mad_i64_i32 v[20:21], s[0:1], v35, s2, v[28:29]
	v_lshl_add_u64 v[20:21], v[20:21], 0, v[192:193]
	global_store_dwordx4 v[20:21], v[16:19], off offset:2048 sc1
	ds_read_b128 v[16:19], v31 offset:4352
	v_and_b32_e32 v23, 0xffff0000, v12
	s_waitcnt lgkmcnt(0)
	v_lshlrev_b32_e32 v20, 16, v16
	v_and_b32_e32 v21, 0xffff0000, v16
	v_pk_mul_f32 v[20:21], v[22:23], v[20:21]
	v_lshlrev_b32_e32 v16, 16, v17
	v_cvt_pk_bf16_f32 v12, v20, v21
	v_and_b32_e32 v17, 0xffff0000, v17
	v_lshlrev_b32_e32 v20, 16, v13
	v_and_b32_e32 v21, 0xffff0000, v13
	v_pk_mul_f32 v[16:17], v[20:21], v[16:17]
	v_lshlrev_b32_e32 v20, 16, v14
	v_cvt_pk_bf16_f32 v13, v16, v17
	v_lshlrev_b32_e32 v16, 16, v18
	v_and_b32_e32 v17, 0xffff0000, v18
	v_and_b32_e32 v21, 0xffff0000, v14
	v_pk_mul_f32 v[16:17], v[20:21], v[16:17]
	v_lshlrev_b32_e32 v18, 16, v15
	v_cvt_pk_bf16_f32 v14, v16, v17
	v_lshlrev_b32_e32 v16, 16, v19
	v_and_b32_e32 v17, 0xffff0000, v19
	v_and_b32_e32 v19, 0xffff0000, v15
	v_pk_mul_f32 v[16:17], v[18:19], v[16:17]
	s_waitcnt vmcnt(6)
; __device__ __forceinline__ unsigned cvt_pk_bf16(float lo, float hi) { f32x2_t v = {lo, hi}; bf16x2_t r = __builtin_convertvector(v, bf16x2_t); return __builtin_bit_cast(unsigned, r); }
; __device__ __forceinline__ float bf_lo(unsigned w) { return __uint_as_float(w << 16); }
; __device__ __forceinline__ float bf_hi(unsigned w) { return __uint_as_float(w & 0xffff0000u); }
; template <int MODE, int SDEPTH, bool SIMPLE>
; __device__ __forceinline__ void attn_body(const Unit& U, char* lds, const int tid) {
;     ...
;     for (int i = 0; i < 8; ++i) { const int row = rb + 4 * i; const long orow = wid * QBLK + row;
;       u32x4 v = *(const u32x4*)(ol + row * OP + cc);
;       if constexpr (MODE != 2) { const u32x4 z = zz[i];
; #pragma unroll
;         for (int q = 0; q < 4; ++q) v[q] = cvt_pk_bf16(bf_lo(v[q]) * bf_lo(z[q]), bf_hi(v[q]) * bf_hi(z[q])); }
;       *(u32x4*)(U.O + orow * U.ldo + cc) = v; } }
; __global__ void __launch_bounds__(512) mega(Args a) {
;     ...
;       for (int i = 0;; ++i) {
;         const int un = i * G + cu; if (un >= NB * 8 * 32) break;
	v_lshlrev_b32_e32 v18, 16, v8
	v_cvt_pk_bf16_f32 v15, v16, v17
	v_mad_i64_i32 v[16:17], s[0:1], v34, s2, v[28:29]
	v_lshl_add_u64 v[16:17], v[16:17], 0, v[192:193]
	global_store_dwordx4 v[16:17], v[12:15], off offset:2048 sc1
	ds_read_b128 v[12:15], v31 offset:5440
	v_and_b32_e32 v19, 0xffff0000, v8
	s_waitcnt lgkmcnt(0)
	v_lshlrev_b32_e32 v16, 16, v12
	v_and_b32_e32 v17, 0xffff0000, v12
	v_pk_mul_f32 v[16:17], v[18:19], v[16:17]
	v_lshlrev_b32_e32 v12, 16, v13
	v_cvt_pk_bf16_f32 v8, v16, v17
	v_and_b32_e32 v13, 0xffff0000, v13
	v_lshlrev_b32_e32 v16, 16, v9
	v_and_b32_e32 v17, 0xffff0000, v9
	v_pk_mul_f32 v[12:13], v[16:17], v[12:13]
	v_lshlrev_b32_e32 v16, 16, v10
	v_cvt_pk_bf16_f32 v9, v12, v13
	v_lshlrev_b32_e32 v12, 16, v14
	v_and_b32_e32 v13, 0xffff0000, v14
	v_and_b32_e32 v17, 0xffff0000, v10
	v_pk_mul_f32 v[12:13], v[16:17], v[12:13]
	v_lshlrev_b32_e32 v14, 16, v11
	v_cvt_pk_bf16_f32 v10, v12, v13
	v_lshlrev_b32_e32 v12, 16, v15
	v_and_b32_e32 v13, 0xffff0000, v15
	v_and_b32_e32 v15, 0xffff0000, v11
	v_pk_mul_f32 v[12:13], v[14:15], v[12:13]
	s_waitcnt vmcnt(6)
	v_lshlrev_b32_e32 v14, 16, v4
	v_cvt_pk_bf16_f32 v11, v12, v13
	v_mad_i64_i32 v[12:13], s[0:1], v33, s2, v[28:29]
	v_lshl_add_u64 v[12:13], v[12:13], 0, v[192:193]
	global_store_dwordx4 v[12:13], v[8:11], off offset:2048 sc1
	ds_read_b128 v[8:11], v31 offset:6528
	v_and_b32_e32 v15, 0xffff0000, v4
	s_waitcnt lgkmcnt(0)
	v_lshlrev_b32_e32 v12, 16, v8
	v_and_b32_e32 v13, 0xffff0000, v8
	v_pk_mul_f32 v[12:13], v[14:15], v[12:13]
	v_lshlrev_b32_e32 v8, 16, v9
	v_cvt_pk_bf16_f32 v4, v12, v13
	v_and_b32_e32 v9, 0xffff0000, v9
	v_lshlrev_b32_e32 v12, 16, v5
	v_and_b32_e32 v13, 0xffff0000, v5
	v_pk_mul_f32 v[8:9], v[12:13], v[8:9]
	v_lshlrev_b32_e32 v12, 16, v6
	v_cvt_pk_bf16_f32 v5, v8, v9
	v_lshlrev_b32_e32 v8, 16, v10
	v_and_b32_e32 v9, 0xffff0000, v10
	v_and_b32_e32 v13, 0xffff0000, v6
	v_pk_mul_f32 v[8:9], v[12:13], v[8:9]
	v_lshlrev_b32_e32 v10, 16, v7
	v_cvt_pk_bf16_f32 v6, v8, v9
	v_lshlrev_b32_e32 v8, 16, v11
	v_and_b32_e32 v9, 0xffff0000, v11
	v_and_b32_e32 v11, 0xffff0000, v7
	v_pk_mul_f32 v[8:9], v[10:11], v[8:9]
	s_waitcnt vmcnt(6)
	v_lshlrev_b32_e32 v10, 16, v0
	v_cvt_pk_bf16_f32 v7, v8, v9
	v_mad_i64_i32 v[8:9], s[0:1], v32, s2, v[28:29]
	v_lshl_add_u64 v[8:9], v[8:9], 0, v[192:193]
	global_store_dwordx4 v[8:9], v[4:7], off offset:2048 sc1
	ds_read_b128 v[4:7], v31 offset:7616
	v_and_b32_e32 v11, 0xffff0000, v0
	s_waitcnt lgkmcnt(0)
	v_lshlrev_b32_e32 v8, 16, v4
	v_and_b32_e32 v9, 0xffff0000, v4
	v_pk_mul_f32 v[8:9], v[10:11], v[8:9]
	v_lshlrev_b32_e32 v4, 16, v5
	v_cvt_pk_bf16_f32 v0, v8, v9
	v_and_b32_e32 v5, 0xffff0000, v5
	v_lshlrev_b32_e32 v8, 16, v1
	v_and_b32_e32 v9, 0xffff0000, v1
	v_pk_mul_f32 v[4:5], v[8:9], v[4:5]
	v_lshlrev_b32_e32 v8, 16, v2
	v_cvt_pk_bf16_f32 v1, v4, v5
	v_lshlrev_b32_e32 v4, 16, v6
	v_and_b32_e32 v5, 0xffff0000, v6
	v_and_b32_e32 v9, 0xffff0000, v2
	v_pk_mul_f32 v[4:5], v[8:9], v[4:5]
	v_lshlrev_b32_e32 v6, 16, v3
	v_cvt_pk_bf16_f32 v2, v4, v5
	v_lshlrev_b32_e32 v4, 16, v7
	v_and_b32_e32 v5, 0xffff0000, v7
	v_and_b32_e32 v7, 0xffff0000, v3
	v_pk_mul_f32 v[4:5], v[6:7], v[4:5]
	s_nop 0
	v_cvt_pk_bf16_f32 v3, v4, v5
	v_mad_i64_i32 v[4:5], s[0:1], v30, s2, v[28:29]
	s_mul_i32 s0, s62, s56
	s_add_i32 s0, s0, s57
	v_lshl_add_u64 v[4:5], v[4:5], 0, v[192:193]
	s_cmpk_gt_i32 s0, 0x1ff
	global_store_dwordx4 v[4:5], v[0:3], off offset:2048 sc1
	s_cbranch_scc1 .Lgq_restore

; __device__ __forceinline__ int opaque_v(int v) { asm volatile("" : "+v"(v)); return v; }
; __global__ void __launch_bounds__(512) mega(Args a) {
;     ...
;       for (int i = 0;; ++i) {
;         const int un = i * G + cu; if (un >= NB * 8 * 32) break;
;         const int h = un & 7, qb = (un >> 3) & 31, b = un >> 8;
;         __syncthreads();
;         att::Unit U{};
;         const size_t tq = (size_t)b * SEQ + qb * 256;
;         U.Q = QBc + ((size_t)(b * 8 + h) * SEQ + qb * 256) * 128; U.K = KBc + (size_t)(b * 2 + (h >> 2)) * SEQ * 128; U.V = VBc + (size_t)(b * 2 + (h >> 2)) * SEQ * 128;
;         U.ldq = 128; U.ldk = 128; U.NT = SEQ / 64;
;         U.O = Y + tq * YW + 1024 + h * 128; U.ldo = YW; U.Z = PROJ + tq * NIN + C_ZB + h * 128; U.ldz = NIN;
;         att::attn_body<0, 2, false>(U, shm, opaque_v(tid));
;       }
.LBB0_217:
	s_setprio 0
	s_mov_b64 s[0:1], 0
